# MLA: DMA source address increments moved from between PV and QK into the vector block
# speedup vs baseline: 1.0296x; 1.0296x over previous
; DI unsigned pk2(float lo, float hi) { const f32x2_t v = {lo, hi}; const bf16x2_t b = __builtin_convertvector(v, bf16x2_t); return __builtin_bit_cast(unsigned, b); }
; #define MLA_DMA(t, slot) do { _Pragma("unroll") for (int i_ = 0; i_ < 4; ++i_) { const bf16_t* src_ = (pisk[i_] ? kbase : vbase) + poff[i_] + (size_t)(t) * pstep[i_]; \
;         __builtin_amdgcn_global_load_lds((const unsigned*)src_, (LAS unsigned*)(lds + (slot) * SLOT + (w + 8 * i_) * 1024), 16, 0, 0); } } while (0)
; DI void mla_attn_phase(LAS unsigned char* lds, const bf16_t* Qg, const bf16_t* Kg, const bf16_t* Vtg, bf16_t* MIX) {
;     ...
;                 if (kt + 2 < NT) MLA_DMA(kt + 2, sl2);
;     ...
;                     const float m_new = fmaxf(m_run, mx), alpha = __builtin_amdgcn_exp2f(m_run - m_new); m_run = m_new;
;                     float sum = 0.f;
; #pragma unroll
;                     for (int i = 0; i < 16; ++i) { s0[i] = __builtin_amdgcn_exp2f(s0[i] - m_new); s1[i] = __builtin_amdgcn_exp2f(s1[i] - m_new); sum += s0[i] + s1[i]; }
;                     l_run = l_run * alpha + sum;
;                     if (__any(alpha != 1.f)) {
; #pragma unroll
;                         for (int mt = 0; mt < 4; ++mt)
; #pragma unroll
;                             for (int i = 0; i < 16; ++i) o[mt][i] *= alpha; }
;                     bf16x8 pf[4];
; #pragma unroll
;                     for (int sp = 0; sp < 2; ++sp) { u32x4 p0, p1;
; #pragma unroll
;                         for (int j = 0; j < 4; ++j) { p0[j] = pk2(s0[8 * sp + 2 * j], s0[8 * sp + 2 * j + 1]); p1[j] = pk2(s1[8 * sp + 2 * j], s1[8 * sp + 2 * j + 1]); }
;                         pf[sp] = __builtin_bit_cast(bf16x8, p0); pf[2 + sp] = __builtin_bit_cast(bf16x8, p1); }
.Lmla_nodma:
	v_lshl_add_u64 v[216:217], v[216:217], 0, s[18:19]
	v_lshl_add_u64 v[214:215], v[214:215], 0, s[20:21]
	v_lshl_add_u64 v[212:213], v[212:213], 0, s[2:3]
	v_lshl_add_u64 v[210:211], v[210:211], 0, s[22:23]
	s_cmp_gt_i32 s40, s39
	s_cbranch_scc1 .Lmla_x
	v_sub_f32_e32 v80, v80, v3
	v_sub_f32_e32 v96, v96, v3
	v_exp_f32_e32 v80, v80
	v_exp_f32_e32 v96, v96
	v_sub_f32_e32 v81, v81, v3
	v_sub_f32_e32 v97, v97, v3
	v_exp_f32_e32 v81, v81
	v_exp_f32_e32 v97, v97
	v_sub_f32_e32 v82, v82, v3
	v_sub_f32_e32 v98, v98, v3
	v_exp_f32_e32 v82, v82
	v_exp_f32_e32 v98, v98
	v_sub_f32_e32 v83, v83, v3
	v_sub_f32_e32 v99, v99, v3
	v_exp_f32_e32 v83, v83
	v_exp_f32_e32 v99, v99
	v_add_f32_e32 v218, v80, v96
	v_sub_f32_e32 v84, v84, v3
	v_add_f32_e32 v218, 0, v218
	v_add_f32_e32 v219, v81, v97
	v_exp_f32_e32 v226, v84
	v_sub_f32_e32 v84, v100, v3
	v_add_f32_e32 v218, v219, v218
	v_add_f32_e32 v219, v82, v98
	v_exp_f32_e32 v100, v84
	v_sub_f32_e32 v84, v85, v3
	v_add_f32_e32 v218, v219, v218
	v_add_f32_e32 v219, v83, v99
	v_exp_f32_e32 v227, v84
	v_sub_f32_e32 v84, v101, v3
	v_sub_f32_e32 v86, v86, v3
	v_exp_f32_e32 v101, v84
	v_add_f32_e32 v84, v219, v218
	v_exp_f32_e32 v218, v86
	v_sub_f32_e32 v86, v102, v3
	v_exp_f32_e32 v102, v86
	v_sub_f32_e32 v86, v87, v3
	v_exp_f32_e32 v87, v86
	v_sub_f32_e32 v86, v103, v3
	v_exp_f32_e32 v103, v86
	v_sub_f32_e32 v86, v88, v3
	v_exp_f32_e32 v88, v86
	v_sub_f32_e32 v86, v104, v3
	v_exp_f32_e32 v104, v86
	v_sub_f32_e32 v86, v89, v3
	v_exp_f32_e32 v89, v86
	v_sub_f32_e32 v86, v105, v3
	v_exp_f32_e32 v105, v86
	v_sub_f32_e32 v86, v90, v3
	v_exp_f32_e32 v90, v86
	v_sub_f32_e32 v86, v106, v3
	v_exp_f32_e32 v106, v86
	v_sub_f32_e32 v86, v91, v3
	v_exp_f32_e32 v91, v86
	v_sub_f32_e32 v86, v107, v3
	v_exp_f32_e32 v107, v86
	v_sub_f32_e32 v86, v92, v3
	v_add_f32_e32 v85, v226, v100
	v_exp_f32_e32 v219, v86
	v_sub_f32_e32 v86, v108, v3
	v_add_f32_e32 v84, v85, v84
	v_add_f32_e32 v85, v227, v101
	v_exp_f32_e32 v108, v86
	v_sub_f32_e32 v86, v93, v3
	v_add_f32_e32 v84, v85, v84
	v_add_f32_e32 v85, v218, v102
	v_exp_f32_e32 v234, v86
	v_sub_f32_e32 v86, v109, v3
	v_add_f32_e32 v84, v85, v84
	v_add_f32_e32 v85, v87, v103
	v_exp_f32_e32 v109, v86
	v_sub_f32_e32 v86, v94, v3
	v_add_f32_e32 v84, v85, v84
	v_add_f32_e32 v85, v88, v104
	v_exp_f32_e32 v235, v86
	v_sub_f32_e32 v86, v110, v3
	v_add_f32_e32 v84, v85, v84
	v_add_f32_e32 v85, v89, v105
	v_exp_f32_e32 v110, v86
	v_sub_f32_e32 v86, v95, v3
	v_add_f32_e32 v84, v85, v84
	v_add_f32_e32 v85, v90, v106
	v_exp_f32_e32 v95, v86
	v_sub_f32_e32 v86, v111, v3
	v_add_f32_e32 v84, v85, v84
	v_add_f32_e32 v85, v91, v107
	v_exp_f32_e32 v111, v86
	v_add_f32_e32 v84, v85, v84
	v_add_f32_e32 v85, v219, v108
	v_add_f32_e32 v84, v85, v84
	v_add_f32_e32 v85, v234, v109
	v_add_f32_e32 v84, v85, v84
	v_add_f32_e32 v85, v235, v110
	v_add_f32_e32 v84, v85, v84
	v_add_f32_e32 v85, v95, v111
	v_add_f32_e32 v236, v85, v84
	v_fmac_f32_e32 v236, v233, v0
	v_cvt_pk_bf16_f32 v80, v80, v81
	v_cvt_pk_bf16_f32 v84, v96, v97
	v_cvt_pk_bf16_f32 v81, v82, v83
	v_cvt_pk_bf16_f32 v85, v98, v99
	v_cvt_pk_bf16_f32 v82, v226, v227
	v_cvt_pk_bf16_f32 v86, v100, v101
	v_cvt_pk_bf16_f32 v83, v218, v87
	v_cvt_pk_bf16_f32 v87, v102, v103
	v_cvt_pk_bf16_f32 v88, v88, v89
	v_cvt_pk_bf16_f32 v92, v104, v105
	v_cvt_pk_bf16_f32 v89, v90, v91
	v_cvt_pk_bf16_f32 v93, v106, v107
	v_cvt_pk_bf16_f32 v90, v219, v234
	v_cvt_pk_bf16_f32 v94, v108, v109
	v_cvt_pk_bf16_f32 v91, v235, v95
	v_cvt_pk_bf16_f32 v95, v110, v111

; #define MLA_DMA(t, slot) do { _Pragma("unroll") for (int i_ = 0; i_ < 4; ++i_) { const bf16_t* src_ = (pisk[i_] ? kbase : vbase) + poff[i_] + (size_t)(t) * pstep[i_]; \
;         __builtin_amdgcn_global_load_lds((const unsigned*)src_, (LAS unsigned*)(lds + (slot) * SLOT + (w + 8 * i_) * 1024), 16, 0, 0); } } while (0)
; DI void mla_attn_phase(LAS unsigned char* lds, const bf16_t* Qg, const bf16_t* Kg, const bf16_t* Vtg, bf16_t* MIX) {
;     ...
;             for (int kt = 0; kt < NT; ++kt) {
;                 const int sl2 = sl == 0 ? 2 : sl - 1;
;                 if (kt + 2 < NT) MLA_DMA(kt + 2, sl2);
;     ...
;                 sl = sl == 2 ? 0 : sl + 1;
.LBB0_371:
	s_add_i32 s41, s41, 1
	s_and_b32 s41, s41, 3
	s_add_i32 s42, s42, 1
	s_add_i32 s40, s40, 64
	s_cmp_eq_u32 s38, s42
	s_cbranch_scc1 .Lmla_exit
	v_mov_b32_e32 v234, v3
	s_branch .LBB0_359
